# SwiGLU epilogue rewritten: weight-row permutation puts a wave's two result groups in adjacent hidden columns, permlane swaps, 8 dwordx4 stores per wave instead of 16 dwordx2
# speedup vs baseline: 1.0180x; 1.0140x over previous
; DI unsigned pack2(float a, float b) { f32x2 v = {a, b}; return __builtin_bit_cast(unsigned, __builtin_convertvector(v, hwbf16x2)); }
; DI void convT(const float* __restrict__ src, int K, int N, int Npad, bf16_t* __restrict__ dst, const float* __restrict__ gain, int mode, char* lds) {
;     ...
;       const int nn = tid >> 2, kc = (tid & 3) * 16, n = n0 + nn;
;       int nrow = n;
;       if (mode == 1) { const int hf = n >= DFF ? 1 : 0, j = n - hf * DFF; nrow = (j >> 4) * 32 + hf * 16 + (j & 15); }
;       u32x4 o0, o1;
;       o0.x = pack2(tile[(kc + 0) * 65 + nn], tile[(kc + 1) * 65 + nn]);
;       o0.y = pack2(tile[(kc + 2) * 65 + nn], tile[(kc + 3) * 65 + nn]);
;       o0.z = pack2(tile[(kc + 4) * 65 + nn], tile[(kc + 5) * 65 + nn]);
;       o0.w = pack2(tile[(kc + 6) * 65 + nn], tile[(kc + 7) * 65 + nn]);
;       o1.x = pack2(tile[(kc + 8) * 65 + nn], tile[(kc + 9) * 65 + nn]);
;       o1.y = pack2(tile[(kc + 10) * 65 + nn], tile[(kc + 11) * 65 + nn]);
;       o1.z = pack2(tile[(kc + 12) * 65 + nn], tile[(kc + 13) * 65 + nn]);
;       o1.w = pack2(tile[(kc + 14) * 65 + nn], tile[(kc + 15) * 65 + nn]);
;       bf16_t* d = dst + (size_t)nrow * K + k0 + kc;
;       *(u32x4*)d = o0; *(u32x4*)(d + 8) = o1;
.LBB0_29:
	s_or_b64 exec, exec, s[42:43]
	s_waitcnt lgkmcnt(0)
	s_barrier
	s_and_saveexec_b64 s[0:1], s[4:5]
	s_cbranch_execz .LBB0_13
	v_add3_u32 v2, v32, v35, v46
	v_cmp_lt_i32_e32 vcc, s54, v2
	v_ashrrev_i32_e32 v23, 31, v22
	s_nop 0
	v_cndmask_b32_e32 v3, 0, v29, vcc
	v_add_lshl_u32 v2, v2, v3, 1
	v_and_b32_e32 v8, 0xffffffe0, v2
	v_bfe_u32 v10, v8, 6, 2
	v_bfe_u32 v11, v8, 5, 1
	v_and_b32_e32 v8, 0xffffff1f, v8
	v_lshl_or_b32 v8, v10, 5, v8
	v_lshl_or_b32 v8, v11, 7, v8
	ds_read2_b32 v[2:3], v34 offset1:65
	ds_read2_b32 v[4:5], v34 offset0:130 offset1:195
	ds_read2_b32 v[6:7], v43 offset0:4 offset1:69
	v_cndmask_b32_e64 v9, 0, 16, vcc
	v_or3_b32 v10, v9, v33, v8
	s_waitcnt lgkmcnt(2)
	v_cvt_pk_bf16_f32 v2, v2, v3
	s_waitcnt lgkmcnt(1)
	v_cvt_pk_bf16_f32 v3, v4, v5
	s_waitcnt lgkmcnt(0)
	v_cvt_pk_bf16_f32 v4, v6, v7
	ds_read2_b32 v[6:7], v43 offset0:134 offset1:199
	ds_read2_b32 v[8:9], v44 offset0:8 offset1:73
	ds_read2_b32 v[12:13], v44 offset0:138 offset1:203
	ds_read2_b32 v[14:15], v45 offset0:12 offset1:77
	ds_read2_b32 v[16:17], v45 offset0:142 offset1:207
	v_ashrrev_i32_e32 v11, 31, v10
	v_lshlrev_b64 v[10:11], 11, v[10:11]
	v_lshl_add_u64 v[10:11], s[38:39], 0, v[10:11]
	v_lshl_add_u64 v[10:11], v[22:23], 1, v[10:11]
	s_waitcnt lgkmcnt(4)
	v_cvt_pk_bf16_f32 v5, v6, v7
	v_lshl_add_u64 v[10:11], v[10:11], 0, v[18:19]
	s_waitcnt lgkmcnt(3)
	v_cvt_pk_bf16_f32 v6, v8, v9
	s_waitcnt lgkmcnt(2)
	v_cvt_pk_bf16_f32 v7, v12, v13
	s_waitcnt lgkmcnt(1)
	v_cvt_pk_bf16_f32 v8, v14, v15
	s_waitcnt lgkmcnt(0)
	v_cvt_pk_bf16_f32 v9, v16, v17
	global_store_dwordx4 v[10:11], v[2:5], off
	global_store_dwordx4 v[10:11], v[6:9], off offset:16
	s_branch .LBB0_13

; DI unsigned pack2(float a, float b) { f32x2 v = {a, b}; return __builtin_bit_cast(unsigned, __builtin_convertvector(v, hwbf16x2)); }
; DI void convT(const float* __restrict__ src, int K, int N, int Npad, bf16_t* __restrict__ dst, const float* __restrict__ gain, int mode, char* lds) {
;     ...
;       const int nn = tid >> 2, kc = (tid & 3) * 16, n = n0 + nn;
;       int nrow = n;
;       if (mode == 1) { const int hf = n >= DFF ? 1 : 0, j = n - hf * DFF; nrow = (j >> 4) * 32 + hf * 16 + (j & 15); }
;       u32x4 o0, o1;
;       o0.x = pack2(tile[(kc + 0) * 65 + nn], tile[(kc + 1) * 65 + nn]);
;       o0.y = pack2(tile[(kc + 2) * 65 + nn], tile[(kc + 3) * 65 + nn]);
;       o0.z = pack2(tile[(kc + 4) * 65 + nn], tile[(kc + 5) * 65 + nn]);
;       o0.w = pack2(tile[(kc + 6) * 65 + nn], tile[(kc + 7) * 65 + nn]);
;       o1.x = pack2(tile[(kc + 8) * 65 + nn], tile[(kc + 9) * 65 + nn]);
;       o1.y = pack2(tile[(kc + 10) * 65 + nn], tile[(kc + 11) * 65 + nn]);
;       o1.z = pack2(tile[(kc + 12) * 65 + nn], tile[(kc + 13) * 65 + nn]);
;       o1.w = pack2(tile[(kc + 14) * 65 + nn], tile[(kc + 15) * 65 + nn]);
;       bf16_t* d = dst + (size_t)nrow * K + k0 + kc;
;       *(u32x4*)d = o0; *(u32x4*)(d + 8) = o1;
.LBB0_64:
	s_or_b64 exec, exec, s[44:45]
	s_waitcnt lgkmcnt(0)
	s_barrier
	s_and_saveexec_b64 s[0:1], s[4:5]
	s_cbranch_execz .LBB0_48
	v_add3_u32 v2, v32, v35, v37
	v_cmp_lt_i32_e32 vcc, s54, v2
	v_add_u32_e32 v9, 0x400, v34
	v_ashrrev_i32_e32 v23, 31, v22
	v_cndmask_b32_e32 v3, 0, v29, vcc
	v_add_lshl_u32 v2, v2, v3, 1
	v_and_b32_e32 v8, 0xffffffe0, v2
	v_bfe_u32 v10, v8, 6, 2
	v_bfe_u32 v11, v8, 5, 1
	v_and_b32_e32 v8, 0xffffff1f, v8
	v_lshl_or_b32 v8, v10, 5, v8
	v_lshl_or_b32 v8, v11, 7, v8
	ds_read2_b32 v[2:3], v34 offset1:65
	ds_read2_b32 v[4:5], v34 offset0:130 offset1:195
	ds_read2_b32 v[6:7], v9 offset0:4 offset1:69
	v_cndmask_b32_e64 v10, 0, 16, vcc
	v_or3_b32 v10, v10, v33, v8
	s_waitcnt lgkmcnt(2)
	v_cvt_pk_bf16_f32 v2, v2, v3
	s_waitcnt lgkmcnt(1)
	v_cvt_pk_bf16_f32 v3, v4, v5
	v_add_u32_e32 v5, 0x800, v34
	s_waitcnt lgkmcnt(0)
	v_cvt_pk_bf16_f32 v4, v6, v7
	ds_read2_b32 v[6:7], v9 offset0:134 offset1:199
	ds_read2_b32 v[8:9], v5 offset0:8 offset1:73
	ds_read2_b32 v[12:13], v5 offset0:138 offset1:203
	v_add_u32_e32 v5, 0xc00, v34
	ds_read2_b32 v[14:15], v5 offset0:12 offset1:77
	ds_read2_b32 v[16:17], v5 offset0:142 offset1:207
	v_ashrrev_i32_e32 v11, 31, v10
	v_lshlrev_b64 v[10:11], 11, v[10:11]
	v_lshl_add_u64 v[10:11], s[38:39], 0, v[10:11]
	v_lshl_add_u64 v[10:11], v[22:23], 1, v[10:11]
	s_waitcnt lgkmcnt(4)
	v_cvt_pk_bf16_f32 v5, v6, v7
	v_lshl_add_u64 v[10:11], v[10:11], 0, v[18:19]
	s_waitcnt lgkmcnt(3)
	v_cvt_pk_bf16_f32 v6, v8, v9
	s_waitcnt lgkmcnt(2)
	v_cvt_pk_bf16_f32 v7, v12, v13
	s_waitcnt lgkmcnt(1)
	v_cvt_pk_bf16_f32 v8, v14, v15
	s_waitcnt lgkmcnt(0)
	v_cvt_pk_bf16_f32 v9, v16, v17
	global_store_dwordx4 v[10:11], v[2:5], off
	global_store_dwordx4 v[10:11], v[6:9], off offset:16
	s_branch .LBB0_48

; DI unsigned pack2(float a, float b) { f32x2 v = {a, b}; return __builtin_bit_cast(unsigned, __builtin_convertvector(v, hwbf16x2)); }
; template <int EPI>
; DI void gemm8_epilogue(const GemmArgs& g, f32x4 (&acc)[2][2][4][2], const int brow, const int bcol, const int wr, const int wc, const int fr, const int fq) {
;     ...
;       if constexpr (EPI == EPI_SWIGLU) {
;         bf16_t* H = (bf16_t*)g.out0;
;         const int hc = (cb >> 1) + fq * 4;
; #pragma unroll
;         for (int m = 0; m < 4; ++m) {
;           float v[4];
; #pragma unroll
;           for (int j = 0; j < 4; ++j) { const float gt = acc[ai][bj][m][0][j], up = acc[ai][bj][m][1][j]; v[j] = gt * up * __builtin_amdgcn_rcpf(1.f + __expf(-gt)); }
;           u32x2 o; o.x = pack2(v[0], v[1]); o.y = pack2(v[2], v[3]);
;           *(u32x2*)&H[(size_t)(r0 + m * 16) * DFF + hc] = o;
;         }
.LBB0_295:
	v_lshl_add_u32 v157, s20, 8, v138
	s_lshl_b32 s21, s21, 7
	s_add_i32 s21, s21, s68
	v_lshl_add_u32 v136, v140, 1, s21
	v_ashrrev_i32_e32 v137, 31, v136
	v_lshl_add_u64 v[136:137], v[136:137], 1, s[60:61]
	s_mov_b64 s[20:21], 0x16000
	s_mov_b64 s[34:35], 0x6e000
	v_mad_i64_i32 v[158:159], vcc, v157, s33, v[136:137]
	v_pk_mul_f32 v[126:127], v[122:123], v[126:127]
	v_pk_mul_f32 v[128:129], v[124:125], v[128:129]
	v_pk_mul_f32 v[94:95], v[90:91], v[94:95]
	v_pk_mul_f32 v[96:97], v[92:93], v[96:97]
	v_mul_f32_e32 v122, 0xbfb8aa3b, v122
	v_mul_f32_e32 v123, 0xbfb8aa3b, v123
	v_mul_f32_e32 v124, 0xbfb8aa3b, v124
	v_mul_f32_e32 v125, 0xbfb8aa3b, v125
	v_mul_f32_e32 v90, 0xbfb8aa3b, v90
	v_mul_f32_e32 v91, 0xbfb8aa3b, v91
	v_mul_f32_e32 v92, 0xbfb8aa3b, v92
	v_mul_f32_e32 v93, 0xbfb8aa3b, v93
	v_exp_f32_e32 v122, v122
	v_exp_f32_e32 v123, v123
	v_exp_f32_e32 v124, v124
	v_exp_f32_e32 v125, v125
	v_exp_f32_e32 v90, v90
	v_exp_f32_e32 v91, v91
	v_exp_f32_e32 v92, v92
	v_exp_f32_e32 v93, v93
	v_add_f32_e32 v122, 1.0, v122
	v_add_f32_e32 v123, 1.0, v123
	v_add_f32_e32 v124, 1.0, v124
	v_add_f32_e32 v125, 1.0, v125
	v_add_f32_e32 v90, 1.0, v90
	v_add_f32_e32 v91, 1.0, v91
	v_add_f32_e32 v92, 1.0, v92
	v_add_f32_e32 v93, 1.0, v93
	v_rcp_f32_e32 v122, v122
	v_rcp_f32_e32 v123, v123
	v_rcp_f32_e32 v124, v124
	v_rcp_f32_e32 v125, v125
	v_rcp_f32_e32 v90, v90
	v_rcp_f32_e32 v91, v91
	v_rcp_f32_e32 v92, v92
	v_rcp_f32_e32 v93, v93
	v_pk_mul_f32 v[126:127], v[126:127], v[122:123]
	v_pk_mul_f32 v[128:129], v[128:129], v[124:125]
	v_pk_mul_f32 v[94:95], v[94:95], v[90:91]
	v_pk_mul_f32 v[96:97], v[96:97], v[92:93]
	v_cvt_pk_bf16_f32 v122, v126, v127
	v_cvt_pk_bf16_f32 v123, v128, v129
	v_cvt_pk_bf16_f32 v124, v94, v95
	v_cvt_pk_bf16_f32 v125, v96, v97
	s_nop 1
	v_permlane32_swap_b32_e32 v122, v124
	v_permlane32_swap_b32_e32 v123, v125
	s_nop 1
	v_permlane16_swap_b32_e32 v122, v124
	v_permlane16_swap_b32_e32 v123, v125
	global_store_dwordx4 v[158:159], v[122:125], off
	v_lshl_add_u64 v[158:159], v[158:159], 0, s[20:21]
	v_pk_mul_f32 v[118:119], v[114:115], v[118:119]
	v_pk_mul_f32 v[120:121], v[116:117], v[120:121]
	v_pk_mul_f32 v[86:87], v[82:83], v[86:87]
	v_pk_mul_f32 v[88:89], v[84:85], v[88:89]
	v_mul_f32_e32 v114, 0xbfb8aa3b, v114
	v_mul_f32_e32 v115, 0xbfb8aa3b, v115
	v_mul_f32_e32 v116, 0xbfb8aa3b, v116
	v_mul_f32_e32 v117, 0xbfb8aa3b, v117
	v_mul_f32_e32 v82, 0xbfb8aa3b, v82
	v_mul_f32_e32 v83, 0xbfb8aa3b, v83
	v_mul_f32_e32 v84, 0xbfb8aa3b, v84
	v_mul_f32_e32 v85, 0xbfb8aa3b, v85
	v_exp_f32_e32 v114, v114
	v_exp_f32_e32 v115, v115
	v_exp_f32_e32 v116, v116
	v_exp_f32_e32 v117, v117
	v_exp_f32_e32 v82, v82
	v_exp_f32_e32 v83, v83
	v_exp_f32_e32 v84, v84
	v_exp_f32_e32 v85, v85
	v_add_f32_e32 v114, 1.0, v114
	v_add_f32_e32 v115, 1.0, v115
	v_add_f32_e32 v116, 1.0, v116
	v_add_f32_e32 v117, 1.0, v117
	v_add_f32_e32 v82, 1.0, v82
	v_add_f32_e32 v83, 1.0, v83
	v_add_f32_e32 v84, 1.0, v84
	v_add_f32_e32 v85, 1.0, v85
	v_rcp_f32_e32 v114, v114
	v_rcp_f32_e32 v115, v115
	v_rcp_f32_e32 v116, v116
	v_rcp_f32_e32 v117, v117
	v_rcp_f32_e32 v82, v82
	v_rcp_f32_e32 v83, v83
	v_rcp_f32_e32 v84, v84
	v_rcp_f32_e32 v85, v85
	v_pk_mul_f32 v[118:119], v[118:119], v[114:115]
	v_pk_mul_f32 v[120:121], v[120:121], v[116:117]
	v_pk_mul_f32 v[86:87], v[86:87], v[82:83]
	v_pk_mul_f32 v[88:89], v[88:89], v[84:85]
	v_cvt_pk_bf16_f32 v114, v118, v119
	v_cvt_pk_bf16_f32 v115, v120, v121
	v_cvt_pk_bf16_f32 v116, v86, v87
	v_cvt_pk_bf16_f32 v117, v88, v89
	s_nop 1
	v_permlane32_swap_b32_e32 v114, v116
	v_permlane32_swap_b32_e32 v115, v117
	s_nop 1
	v_permlane16_swap_b32_e32 v114, v116
	v_permlane16_swap_b32_e32 v115, v117
	global_store_dwordx4 v[158:159], v[114:117], off
	v_lshl_add_u64 v[158:159], v[158:159], 0, s[20:21]
	v_pk_mul_f32 v[110:111], v[106:107], v[110:111]
	v_pk_mul_f32 v[112:113], v[108:109], v[112:113]
	v_pk_mul_f32 v[78:79], v[74:75], v[78:79]
	v_pk_mul_f32 v[80:81], v[76:77], v[80:81]
	v_mul_f32_e32 v106, 0xbfb8aa3b, v106
	v_mul_f32_e32 v107, 0xbfb8aa3b, v107
	v_mul_f32_e32 v108, 0xbfb8aa3b, v108
	v_mul_f32_e32 v109, 0xbfb8aa3b, v109
	v_mul_f32_e32 v74, 0xbfb8aa3b, v74
	v_mul_f32_e32 v75, 0xbfb8aa3b, v75
	v_mul_f32_e32 v76, 0xbfb8aa3b, v76
	v_mul_f32_e32 v77, 0xbfb8aa3b, v77
	v_exp_f32_e32 v106, v106
	v_exp_f32_e32 v107, v107
	v_exp_f32_e32 v108, v108
	v_exp_f32_e32 v109, v109
	v_exp_f32_e32 v74, v74
	v_exp_f32_e32 v75, v75
	v_exp_f32_e32 v76, v76
	v_exp_f32_e32 v77, v77
	v_add_f32_e32 v106, 1.0, v106
	v_add_f32_e32 v107, 1.0, v107
	v_add_f32_e32 v108, 1.0, v108
	v_add_f32_e32 v109, 1.0, v109
	v_add_f32_e32 v74, 1.0, v74
	v_add_f32_e32 v75, 1.0, v75
	v_add_f32_e32 v76, 1.0, v76
	v_add_f32_e32 v77, 1.0, v77
	v_rcp_f32_e32 v106, v106
	v_rcp_f32_e32 v107, v107
	v_rcp_f32_e32 v108, v108
	v_rcp_f32_e32 v109, v109
	v_rcp_f32_e32 v74, v74
	v_rcp_f32_e32 v75, v75
	v_rcp_f32_e32 v76, v76
	v_rcp_f32_e32 v77, v77
	v_pk_mul_f32 v[110:111], v[110:111], v[106:107]
	v_pk_mul_f32 v[112:113], v[112:113], v[108:109]
	v_pk_mul_f32 v[78:79], v[78:79], v[74:75]
	v_pk_mul_f32 v[80:81], v[80:81], v[76:77]
	v_cvt_pk_bf16_f32 v106, v110, v111
	v_cvt_pk_bf16_f32 v107, v112, v113
	v_cvt_pk_bf16_f32 v108, v78, v79
	v_cvt_pk_bf16_f32 v109, v80, v81
	s_nop 1
	v_permlane32_swap_b32_e32 v106, v108
	v_permlane32_swap_b32_e32 v107, v109
	s_nop 1
	v_permlane16_swap_b32_e32 v106, v108
	v_permlane16_swap_b32_e32 v107, v109
	global_store_dwordx4 v[158:159], v[106:109], off
	v_lshl_add_u64 v[158:159], v[158:159], 0, s[20:21]
	v_pk_mul_f32 v[102:103], v[98:99], v[102:103]
	v_pk_mul_f32 v[104:105], v[100:101], v[104:105]
	v_pk_mul_f32 v[70:71], v[66:67], v[70:71]
	v_pk_mul_f32 v[72:73], v[68:69], v[72:73]
; DI unsigned pack2(float a, float b) { f32x2 v = {a, b}; return __builtin_bit_cast(unsigned, __builtin_convertvector(v, hwbf16x2)); }
; template <int EPI>
; DI void gemm8_epilogue(const GemmArgs& g, f32x4 (&acc)[2][2][4][2], const int brow, const int bcol, const int wr, const int wc, const int fr, const int fq) {
;     ...
;       if constexpr (EPI == EPI_SWIGLU) {
;         bf16_t* H = (bf16_t*)g.out0;
;         const int hc = (cb >> 1) + fq * 4;
; #pragma unroll
;         for (int m = 0; m < 4; ++m) {
;           float v[4];
; #pragma unroll
;           for (int j = 0; j < 4; ++j) { const float gt = acc[ai][bj][m][0][j], up = acc[ai][bj][m][1][j]; v[j] = gt * up * __builtin_amdgcn_rcpf(1.f + __expf(-gt)); }
;           u32x2 o; o.x = pack2(v[0], v[1]); o.y = pack2(v[2], v[3]);
;           *(u32x2*)&H[(size_t)(r0 + m * 16) * DFF + hc] = o;
;         }
	v_mul_f32_e32 v98, 0xbfb8aa3b, v98
	v_mul_f32_e32 v99, 0xbfb8aa3b, v99
	v_mul_f32_e32 v100, 0xbfb8aa3b, v100
	v_mul_f32_e32 v101, 0xbfb8aa3b, v101
	v_mul_f32_e32 v66, 0xbfb8aa3b, v66
	v_mul_f32_e32 v67, 0xbfb8aa3b, v67
	v_mul_f32_e32 v68, 0xbfb8aa3b, v68
	v_mul_f32_e32 v69, 0xbfb8aa3b, v69
	v_exp_f32_e32 v98, v98
	v_exp_f32_e32 v99, v99
	v_exp_f32_e32 v100, v100
	v_exp_f32_e32 v101, v101
	v_exp_f32_e32 v66, v66
	v_exp_f32_e32 v67, v67
	v_exp_f32_e32 v68, v68
	v_exp_f32_e32 v69, v69
	v_add_f32_e32 v98, 1.0, v98
	v_add_f32_e32 v99, 1.0, v99
	v_add_f32_e32 v100, 1.0, v100
	v_add_f32_e32 v101, 1.0, v101
	v_add_f32_e32 v66, 1.0, v66
	v_add_f32_e32 v67, 1.0, v67
	v_add_f32_e32 v68, 1.0, v68
	v_add_f32_e32 v69, 1.0, v69
	v_rcp_f32_e32 v98, v98
	v_rcp_f32_e32 v99, v99
	v_rcp_f32_e32 v100, v100
	v_rcp_f32_e32 v101, v101
	v_rcp_f32_e32 v66, v66
	v_rcp_f32_e32 v67, v67
	v_rcp_f32_e32 v68, v68
	v_rcp_f32_e32 v69, v69
	v_pk_mul_f32 v[102:103], v[102:103], v[98:99]
	v_pk_mul_f32 v[104:105], v[104:105], v[100:101]
	v_pk_mul_f32 v[70:71], v[70:71], v[66:67]
	v_pk_mul_f32 v[72:73], v[72:73], v[68:69]
	v_cvt_pk_bf16_f32 v98, v102, v103
	v_cvt_pk_bf16_f32 v99, v104, v105
	v_cvt_pk_bf16_f32 v100, v70, v71
	v_cvt_pk_bf16_f32 v101, v72, v73
	s_nop 1
	v_permlane32_swap_b32_e32 v98, v100
	v_permlane32_swap_b32_e32 v99, v101
	s_nop 1
	v_permlane16_swap_b32_e32 v98, v100
	v_permlane16_swap_b32_e32 v99, v101
	global_store_dwordx4 v[158:159], v[98:101], off
	v_lshl_add_u64 v[158:159], v[158:159], 0, s[34:35]
	v_pk_mul_f32 v[62:63], v[58:59], v[62:63]
	v_pk_mul_f32 v[64:65], v[60:61], v[64:65]
	v_pk_mul_f32 v[30:31], v[26:27], v[30:31]
	v_pk_mul_f32 v[32:33], v[28:29], v[32:33]
	v_mul_f32_e32 v58, 0xbfb8aa3b, v58
	v_mul_f32_e32 v59, 0xbfb8aa3b, v59
	v_mul_f32_e32 v60, 0xbfb8aa3b, v60
	v_mul_f32_e32 v61, 0xbfb8aa3b, v61
	v_mul_f32_e32 v26, 0xbfb8aa3b, v26
	v_mul_f32_e32 v27, 0xbfb8aa3b, v27
	v_mul_f32_e32 v28, 0xbfb8aa3b, v28
	v_mul_f32_e32 v29, 0xbfb8aa3b, v29
	v_exp_f32_e32 v58, v58
	v_exp_f32_e32 v59, v59
	v_exp_f32_e32 v60, v60
	v_exp_f32_e32 v61, v61
	v_exp_f32_e32 v26, v26
	v_exp_f32_e32 v27, v27
	v_exp_f32_e32 v28, v28
	v_exp_f32_e32 v29, v29
	v_add_f32_e32 v58, 1.0, v58
	v_add_f32_e32 v59, 1.0, v59
	v_add_f32_e32 v60, 1.0, v60
	v_add_f32_e32 v61, 1.0, v61
	v_add_f32_e32 v26, 1.0, v26
	v_add_f32_e32 v27, 1.0, v27
	v_add_f32_e32 v28, 1.0, v28
	v_add_f32_e32 v29, 1.0, v29
	v_rcp_f32_e32 v58, v58
	v_rcp_f32_e32 v59, v59
	v_rcp_f32_e32 v60, v60
	v_rcp_f32_e32 v61, v61
	v_rcp_f32_e32 v26, v26
	v_rcp_f32_e32 v27, v27
	v_rcp_f32_e32 v28, v28
	v_rcp_f32_e32 v29, v29
	v_pk_mul_f32 v[62:63], v[62:63], v[58:59]
	v_pk_mul_f32 v[64:65], v[64:65], v[60:61]
	v_pk_mul_f32 v[30:31], v[30:31], v[26:27]
	v_pk_mul_f32 v[32:33], v[32:33], v[28:29]
	v_cvt_pk_bf16_f32 v58, v62, v63
	v_cvt_pk_bf16_f32 v59, v64, v65
	v_cvt_pk_bf16_f32 v60, v30, v31
	v_cvt_pk_bf16_f32 v61, v32, v33
	s_nop 1
	v_permlane32_swap_b32_e32 v58, v60
	v_permlane32_swap_b32_e32 v59, v61
	s_nop 1
	v_permlane16_swap_b32_e32 v58, v60
	v_permlane16_swap_b32_e32 v59, v61
	global_store_dwordx4 v[158:159], v[58:61], off
	v_lshl_add_u64 v[158:159], v[158:159], 0, s[20:21]
	v_pk_mul_f32 v[54:55], v[50:51], v[54:55]
	v_pk_mul_f32 v[56:57], v[52:53], v[56:57]
	v_pk_mul_f32 v[22:23], v[18:19], v[22:23]
	v_pk_mul_f32 v[24:25], v[20:21], v[24:25]
	v_mul_f32_e32 v50, 0xbfb8aa3b, v50
	v_mul_f32_e32 v51, 0xbfb8aa3b, v51
	v_mul_f32_e32 v52, 0xbfb8aa3b, v52
	v_mul_f32_e32 v53, 0xbfb8aa3b, v53
	v_mul_f32_e32 v18, 0xbfb8aa3b, v18
	v_mul_f32_e32 v19, 0xbfb8aa3b, v19
	v_mul_f32_e32 v20, 0xbfb8aa3b, v20
	v_mul_f32_e32 v21, 0xbfb8aa3b, v21
	v_exp_f32_e32 v50, v50
	v_exp_f32_e32 v51, v51
	v_exp_f32_e32 v52, v52
	v_exp_f32_e32 v53, v53
	v_exp_f32_e32 v18, v18
	v_exp_f32_e32 v19, v19
	v_exp_f32_e32 v20, v20
	v_exp_f32_e32 v21, v21
	v_add_f32_e32 v50, 1.0, v50
	v_add_f32_e32 v51, 1.0, v51
	v_add_f32_e32 v52, 1.0, v52
	v_add_f32_e32 v53, 1.0, v53
	v_add_f32_e32 v18, 1.0, v18
	v_add_f32_e32 v19, 1.0, v19
	v_add_f32_e32 v20, 1.0, v20
	v_add_f32_e32 v21, 1.0, v21
	v_rcp_f32_e32 v50, v50
; DI unsigned pack2(float a, float b) { f32x2 v = {a, b}; return __builtin_bit_cast(unsigned, __builtin_convertvector(v, hwbf16x2)); }
; template <int EPI>
; DI void gemm8_epilogue(const GemmArgs& g, f32x4 (&acc)[2][2][4][2], const int brow, const int bcol, const int wr, const int wc, const int fr, const int fq) {
;     ...
;       if constexpr (EPI == EPI_SWIGLU) {
;         bf16_t* H = (bf16_t*)g.out0;
;         const int hc = (cb >> 1) + fq * 4;
; #pragma unroll
;         for (int m = 0; m < 4; ++m) {
;           float v[4];
; #pragma unroll
;           for (int j = 0; j < 4; ++j) { const float gt = acc[ai][bj][m][0][j], up = acc[ai][bj][m][1][j]; v[j] = gt * up * __builtin_amdgcn_rcpf(1.f + __expf(-gt)); }
;           u32x2 o; o.x = pack2(v[0], v[1]); o.y = pack2(v[2], v[3]);
;           *(u32x2*)&H[(size_t)(r0 + m * 16) * DFF + hc] = o;
;         }
	v_rcp_f32_e32 v51, v51
	v_rcp_f32_e32 v52, v52
	v_rcp_f32_e32 v53, v53
	v_rcp_f32_e32 v18, v18
	v_rcp_f32_e32 v19, v19
	v_rcp_f32_e32 v20, v20
	v_rcp_f32_e32 v21, v21
	v_pk_mul_f32 v[54:55], v[54:55], v[50:51]
	v_pk_mul_f32 v[56:57], v[56:57], v[52:53]
	v_pk_mul_f32 v[22:23], v[22:23], v[18:19]
	v_pk_mul_f32 v[24:25], v[24:25], v[20:21]
	v_cvt_pk_bf16_f32 v50, v54, v55
	v_cvt_pk_bf16_f32 v51, v56, v57
	v_cvt_pk_bf16_f32 v52, v22, v23
	v_cvt_pk_bf16_f32 v53, v24, v25
	s_nop 1
	v_permlane32_swap_b32_e32 v50, v52
	v_permlane32_swap_b32_e32 v51, v53
	s_nop 1
	v_permlane16_swap_b32_e32 v50, v52
	v_permlane16_swap_b32_e32 v51, v53
	global_store_dwordx4 v[158:159], v[50:53], off
	v_lshl_add_u64 v[158:159], v[158:159], 0, s[20:21]
	v_pk_mul_f32 v[46:47], v[42:43], v[46:47]
	v_pk_mul_f32 v[48:49], v[44:45], v[48:49]
	v_pk_mul_f32 v[14:15], v[10:11], v[14:15]
	v_pk_mul_f32 v[16:17], v[12:13], v[16:17]
	v_mul_f32_e32 v42, 0xbfb8aa3b, v42
	v_mul_f32_e32 v43, 0xbfb8aa3b, v43
	v_mul_f32_e32 v44, 0xbfb8aa3b, v44
	v_mul_f32_e32 v45, 0xbfb8aa3b, v45
	v_mul_f32_e32 v10, 0xbfb8aa3b, v10
	v_mul_f32_e32 v11, 0xbfb8aa3b, v11
	v_mul_f32_e32 v12, 0xbfb8aa3b, v12
	v_mul_f32_e32 v13, 0xbfb8aa3b, v13
	v_exp_f32_e32 v42, v42
	v_exp_f32_e32 v43, v43
	v_exp_f32_e32 v44, v44
	v_exp_f32_e32 v45, v45
	v_exp_f32_e32 v10, v10
	v_exp_f32_e32 v11, v11
	v_exp_f32_e32 v12, v12
	v_exp_f32_e32 v13, v13
	v_add_f32_e32 v42, 1.0, v42
	v_add_f32_e32 v43, 1.0, v43
	v_add_f32_e32 v44, 1.0, v44
	v_add_f32_e32 v45, 1.0, v45
	v_add_f32_e32 v10, 1.0, v10
	v_add_f32_e32 v11, 1.0, v11
	v_add_f32_e32 v12, 1.0, v12
	v_add_f32_e32 v13, 1.0, v13
	v_rcp_f32_e32 v42, v42
	v_rcp_f32_e32 v43, v43
	v_rcp_f32_e32 v44, v44
	v_rcp_f32_e32 v45, v45
	v_rcp_f32_e32 v10, v10
	v_rcp_f32_e32 v11, v11
	v_rcp_f32_e32 v12, v12
	v_rcp_f32_e32 v13, v13
	v_pk_mul_f32 v[46:47], v[46:47], v[42:43]
	v_pk_mul_f32 v[48:49], v[48:49], v[44:45]
	v_pk_mul_f32 v[14:15], v[14:15], v[10:11]
	v_pk_mul_f32 v[16:17], v[16:17], v[12:13]
	v_cvt_pk_bf16_f32 v42, v46, v47
	v_cvt_pk_bf16_f32 v43, v48, v49
	v_cvt_pk_bf16_f32 v44, v14, v15
	v_cvt_pk_bf16_f32 v45, v16, v17
	s_nop 1
	v_permlane32_swap_b32_e32 v42, v44
	v_permlane32_swap_b32_e32 v43, v45
	s_nop 1
	v_permlane16_swap_b32_e32 v42, v44
	v_permlane16_swap_b32_e32 v43, v45
	global_store_dwordx4 v[158:159], v[42:45], off
	v_lshl_add_u64 v[158:159], v[158:159], 0, s[20:21]
	v_pk_mul_f32 v[38:39], v[34:35], v[38:39]
	v_pk_mul_f32 v[40:41], v[36:37], v[40:41]
	v_pk_mul_f32 v[6:7], v[2:3], v[6:7]
	v_pk_mul_f32 v[8:9], v[4:5], v[8:9]
	v_mul_f32_e32 v34, 0xbfb8aa3b, v34
	v_mul_f32_e32 v35, 0xbfb8aa3b, v35
	v_mul_f32_e32 v36, 0xbfb8aa3b, v36
	v_mul_f32_e32 v37, 0xbfb8aa3b, v37
	v_mul_f32_e32 v2, 0xbfb8aa3b, v2
	v_mul_f32_e32 v3, 0xbfb8aa3b, v3
	v_mul_f32_e32 v4, 0xbfb8aa3b, v4
	v_mul_f32_e32 v5, 0xbfb8aa3b, v5
	v_exp_f32_e32 v34, v34
	v_exp_f32_e32 v35, v35
	v_exp_f32_e32 v36, v36
	v_exp_f32_e32 v37, v37
	v_exp_f32_e32 v2, v2
	v_exp_f32_e32 v3, v3
	v_exp_f32_e32 v4, v4
	v_exp_f32_e32 v5, v5
	v_add_f32_e32 v34, 1.0, v34
	v_add_f32_e32 v35, 1.0, v35
	v_add_f32_e32 v36, 1.0, v36
	v_add_f32_e32 v37, 1.0, v37
	v_add_f32_e32 v2, 1.0, v2
	v_add_f32_e32 v3, 1.0, v3
	v_add_f32_e32 v4, 1.0, v4
	v_add_f32_e32 v5, 1.0, v5
	v_rcp_f32_e32 v34, v34
	v_rcp_f32_e32 v35, v35
	v_rcp_f32_e32 v36, v36
	v_rcp_f32_e32 v37, v37
	v_rcp_f32_e32 v2, v2
	v_rcp_f32_e32 v3, v3
	v_rcp_f32_e32 v4, v4
	v_rcp_f32_e32 v5, v5
	v_pk_mul_f32 v[38:39], v[38:39], v[34:35]
	v_pk_mul_f32 v[40:41], v[40:41], v[36:37]
	v_pk_mul_f32 v[6:7], v[6:7], v[2:3]
	v_pk_mul_f32 v[8:9], v[8:9], v[4:5]
	v_cvt_pk_bf16_f32 v34, v38, v39
	v_cvt_pk_bf16_f32 v35, v40, v41
	v_cvt_pk_bf16_f32 v36, v6, v7
	v_cvt_pk_bf16_f32 v37, v8, v9
	s_nop 1
	v_permlane32_swap_b32_e32 v34, v36
	v_permlane32_swap_b32_e32 v35, v37
	s_nop 1
	v_permlane16_swap_b32_e32 v34, v36
	v_permlane16_swap_b32_e32 v35, v37
	global_store_dwordx4 v[158:159], v[34:37], off
	s_mov_b64 s[34:35], -1
	s_andn2_b64 vcc, exec, s[46:47]
	s_cbranch_vccnz .LBB0_288
	s_andn2_b64 vcc, exec, s[0:1]
	s_cbranch_vccnz .LBB0_287
	s_barrier
	s_branch .LBB0_287
